# v28 with the GEMM phase prologues de-serialised: K-tile-1 LDS-DMA loads issued before the wait/barrier that retires K-tile 0
# baseline (speedup 1.0000x reference)
.LBB0_176:
	s_and_b64 s[6:7], s[28:29], exec
	v_bfe_u32 v228, v11, 4, 2
	s_movk_i32 s3, 0x800
	v_and_b32_e32 v67, 15, v11
	v_readlane_b32 s6, v241, 59
	v_lshlrev_b32_e32 v17, 4, v228
	v_lshlrev_b32_e32 v11, 2, v11
	s_cselect_b32 s50, s3, 0x500
	s_cselect_b32 s54, 8, 5
	s_and_b32 s3, s10, 3
	s_lshl_b32 s56, s6, 6
	v_lshl_or_b32 v17, v67, 6, v17
	s_lshl_b32 s6, s6, 13
	v_and_b32_e32 v11, 32, v11
	s_add_i32 m0, s95, 0x18000
	v_lshl_add_u64 v[8:9], v[8:9], 0, s[18:19]
	v_bitop3_b32 v18, v17, s6, v11 bitop3:0xde
	s_lshl_b32 s6, s3, 12
	global_load_lds_dwordx4 v[8:9], off
	v_lshl_add_u64 v[4:5], v[4:5], 0, s[18:19]
	s_add_i32 m0, s95, 0x1a000
	s_add_i32 s63, s95, 0x8000
	s_add_i32 s11, s95, 0xa000
	v_bitop3_b32 v229, v17, s6, v11 bitop3:0xde
	global_load_lds_dwordx4 v[4:5], off
	v_lshl_add_u64 v[2:3], v[2:3], 0, s[18:19]
	s_mov_b32 m0, s63
	s_add_u32 s6, s30, 0x40080
	global_load_lds_dwordx4 v[2:3], off
	v_lshl_add_u64 v[2:3], v[6:7], 0, s[18:19]
	s_mov_b32 m0, s11
	s_addc_u32 s7, s31, 0
	global_load_lds_dwordx4 v[2:3], off
	s_add_i32 m0, s95, 0x1c000
	v_lshl_add_u64 v[2:3], s[6:7], 0, v[148:149]
	global_load_lds_dwordx4 v[2:3], off
	v_lshl_add_u64 v[2:3], s[6:7], 0, v[150:151]
	s_add_i32 m0, s95, 0x1e000
	s_cmpk_lt_u32 s1, 0x100
	global_load_lds_dwordx4 v[2:3], off
	s_waitcnt vmcnt(8)
	s_barrier
	s_cselect_b64 s[6:7], -1, 0
	s_lshr_b32 s1, s78, 3
	s_lshl_b32 s65, s3, 6
	v_writelane_b32 v241, s1, 60
	s_lshl_b32 s1, s0, 2
	s_and_b64 s[16:17], s[28:29], exec
	s_cselect_b32 s22, 10, 8
	s_abs_i32 s23, s1
	v_cvt_f32_u32_e32 v2, s23
	s_mov_b32 s83, s1
	v_and_b32_e32 v3, 1, v10
	s_bfe_i32 s0, s0, 0x1001d
	v_rcp_iflag_f32_e32 v2, v2
	v_writelane_b32 v241, s0, 61
	s_sub_i32 s0, 0, s23
	s_waitcnt vmcnt(6)
	v_mul_f32_e32 v2, 0x4f7ffffe, v2
	v_cvt_u32_f32_e32 v2, v2
	s_mov_b32 s51, 0
	v_mov_b32_e32 v153, v185
	v_mov_b32_e32 v155, v185
	v_readfirstlane_b32 s1, v2
	v_lshlrev_b32_e32 v2, 14, v10
	v_and_b32_e32 v2, 0xffff8000, v2
	v_lshl_add_u32 v2, v12, 11, v2
	v_lshl_or_b32 v2, v3, 6, v2
	v_lshl_add_u32 v152, v13, 1, v2
	v_lshlrev_b32_e32 v2, 14, v14
	v_and_b32_e32 v2, 0xffff8000, v2
	s_mul_i32 s0, s0, s1
	v_lshl_add_u32 v2, v15, 11, v2
	v_and_b32_e32 v3, 1, v14
	s_mul_hi_u32 s0, s1, s0
	v_lshl_or_b32 v2, v3, 6, v2
	s_add_i32 s0, s1, s0
	v_lshl_add_u32 v154, v16, 1, v2
	v_add_u32_e32 v230, 0, v18
	v_mov_b64_e32 v[156:157], s[78:79]
	s_movk_i32 s44, 0x4000
	s_movk_i32 s45, 0x2000
	s_movk_i32 s58, 0x6000
	s_movk_i32 s78, 0x3fff
	s_barrier
	v_writelane_b32 v241, s0, 62
	s_branch .LBB0_179

.LBB0_266:
	v_bfe_i32 v4, v14, 27, 1
	v_lshlrev_b32_e32 v2, 4, v14
	v_lshrrev_b32_e32 v4, 22, v4
	v_add_u32_e32 v4, v2, v4
	v_and_b32_e32 v4, 0xfffffc00, v4
	v_sub_u32_e32 v4, v2, v4
	v_ashrrev_i32_e32 v3, 31, v14
	v_lshrrev_b32_e32 v5, 4, v4
	v_lshrrev_b32_e32 v3, 26, v3
	v_bitop3_b32 v4, v5, v4, 32 bitop3:0x6c
	v_add_u32_e32 v3, v14, v3
	v_ashrrev_i32_e32 v6, 31, v4
	v_ashrrev_i32_e32 v3, 6, v3
	v_lshrrev_b32_e32 v6, 26, v6
	v_lshlrev_b32_e32 v5, 3, v3
	v_add_u32_e32 v6, v4, v6
	v_lshlrev_b32_e32 v3, 5, v3
	v_and_b32_e32 v5, 0x7ffffff0, v5
	v_ashrrev_i32_e32 v7, 6, v6
	v_and_b32_e32 v15, 32, v3
	v_and_b32_e32 v3, 0xc0, v6
	v_add_u32_e32 v5, v7, v5
	v_sub_u32_e32 v3, v4, v3
	v_ashrrev_i16_sdwa v3, v221, sext(v3) dst_sel:DWORD dst_unused:UNUSED_PAD src0_sel:DWORD src1_sel:BYTE_0
	v_mul_lo_u32 v17, v5, s0
	v_bfe_i32 v16, v3, 0, 16
	v_or_b32_e32 v3, v17, v15
	v_add_u32_e32 v2, 0x2000, v2
	v_add_lshl_u32 v184, v3, v16, 1
	v_ashrrev_i32_e32 v3, 31, v2
	v_lshrrev_b32_e32 v3, 22, v3
	v_add_u32_e32 v3, v2, v3
	v_ashrrev_i32_e32 v3, 10, v3
	v_mul_i32_i24_e32 v4, 0x400, v3
	v_sub_u32_e32 v2, v2, v4
	v_lshrrev_b32_e32 v4, 4, v2
	s_ashr_i32 s17, s10, 6
	s_lshl_b32 s78, s0, 8
	s_ashr_i32 s22, s7, 2
	v_readlane_b32 s2, v242, 11
	s_ashr_i32 s1, s10, 8
	v_bitop3_b32 v2, v4, v2, 32 bitop3:0x6c
	s_lshl_b64 s[66:67], s[78:79], 1
	s_lshl_b32 s56, s17, 10
	s_add_i32 s25, s22, 64
	v_readlane_b32 s3, v242, 12
	s_andn2_b64 s[2:3], s[2:3], s[100:101]
	v_ashrrev_i32_e32 v5, 31, v2
	s_and_b64 s[22:23], s[2:3], exec
	v_lshrrev_b32_e32 v5, 26, v5
	v_readlane_b32 s22, v242, 60
	v_lshlrev_b32_e32 v4, 3, v3
	v_add_u32_e32 v5, v2, v5
	s_cselect_b32 s65, s22, s25
	s_and_b32 s7, s7, 3
	v_and_b32_e32 v4, 0x7ffffff0, v4
	v_ashrrev_i32_e32 v6, 6, v5
	s_and_b64 s[22:23], s[2:3], exec
	v_readlane_b32 s2, v242, 61
	v_add_u32_e32 v4, v6, v4
	s_cselect_b32 s85, s2, s7
	s_ashr_i32 s7, s65, 31
	v_mul_lo_u32 v20, v4, s0
	s_mul_hi_u32 s22, s66, s65
	s_mul_i32 s7, s66, s7
	s_bfe_u32 s0, s0, 0x10017
	s_add_i32 s7, s22, s7
	s_mul_i32 s22, s0, s65
	s_add_i32 s7, s7, s22
	s_mul_i32 s22, s66, s65
	s_add_u32 s25, s36, s22
	s_addc_u32 s7, s37, s7
	s_ashr_i32 s22, s85, 31
	s_mul_hi_u32 s23, s66, s85
	s_mul_i32 s22, s66, s22
	s_add_i32 s22, s23, s22
	s_mul_i32 s0, s0, s85
	s_add_i32 s22, s22, s0
	s_mul_i32 s0, s66, s85
	s_add_u32 s0, s20, s0
	v_lshlrev_b32_e32 v3, 5, v3
	s_addc_u32 s22, s21, s22
	v_and_b32_e32 v18, 32, v3
	v_and_b32_e32 v3, 0xc0, v5
	s_add_u32 s28, s0, s30
	v_sub_u32_e32 v2, v2, v3
	s_addc_u32 s29, s22, s31
	s_add_i32 s63, s56, 0
	v_ashrrev_i16_sdwa v2, v221, sext(v2) dst_sel:DWORD dst_unused:UNUSED_PAD src0_sel:DWORD src1_sel:BYTE_0
	s_add_i32 m0, s63, 0x10000
	v_bfe_i32 v19, v2, 0, 16
	v_or_b32_e32 v2, v20, v18
	global_load_lds_dwordx4 v184, s[28:29]
	s_add_i32 m0, s63, 0x12000
	v_add_lshl_u32 v144, v2, v19, 1
	s_add_u32 s22, s28, s78
	global_load_lds_dwordx4 v144, s[28:29]
	s_addc_u32 s23, s29, 0
	s_add_i32 m0, s63, 0x14000
	v_mov_b32_e32 v145, v185
	global_load_lds_dwordx4 v184, s[22:23]
	s_add_i32 m0, s63, 0x16000
	s_add_u32 s34, s25, s30
	s_addc_u32 s35, s7, s31
	s_add_i32 s55, s63, 0x2000
	v_lshl_add_u64 v[6:7], s[22:23], 0, v[184:185]
	v_lshl_add_u64 v[8:9], s[22:23], 0, v[144:145]
	global_load_lds_dwordx4 v144, s[22:23]
	s_mov_b32 m0, s63
	s_add_u32 s22, s34, s78
	global_load_lds_dwordx4 v184, s[34:35]
	s_mov_b32 m0, s55
	s_addc_u32 s23, s35, 0
	s_add_i32 s82, s63, 0x4000
	global_load_lds_dwordx4 v144, s[34:35]
	s_mov_b32 m0, s82
	s_add_i32 s83, s63, 0x6000
	global_load_lds_dwordx4 v184, s[22:23]
	s_mov_b32 m0, s83
	s_cmp_eq_u32 s1, 1
	global_load_lds_dwordx4 v144, s[22:23]
	v_lshl_add_u64 v[2:3], s[28:29], 0, v[184:185]
	v_lshl_add_u64 v[4:5], s[28:29], 0, v[144:145]
	v_lshl_add_u64 v[10:11], s[34:35], 0, v[184:185]
	v_lshl_add_u64 v[12:13], s[34:35], 0, v[144:145]
	s_cselect_b64 s[76:77], -1, 0
	s_add_i32 m0, s63, 0x18000
	v_lshl_add_u64 v[244:245], v[2:3], 0, s[18:19]
	s_nop 0
	global_load_lds_dwordx4 v[244:245], off
	s_add_i32 m0, s63, 0x1a000
	v_lshl_add_u64 v[244:245], v[4:5], 0, s[18:19]
	s_nop 0
	global_load_lds_dwordx4 v[244:245], off
	s_add_i32 m0, s63, 0x8000
	v_lshl_add_u64 v[244:245], v[10:11], 0, s[18:19]
	s_nop 0
	global_load_lds_dwordx4 v[244:245], off
	s_add_i32 m0, s63, 0xa000
	v_lshl_add_u64 v[244:245], v[12:13], 0, s[18:19]
	s_nop 0
	global_load_lds_dwordx4 v[244:245], off
	s_add_i32 m0, s63, 0x1c000
	v_lshl_add_u64 v[244:245], v[6:7], 0, s[18:19]
	s_nop 0
	global_load_lds_dwordx4 v[244:245], off
	s_add_i32 m0, s63, 0x1e000
	v_lshl_add_u64 v[244:245], v[8:9], 0, s[18:19]
	s_nop 0
	global_load_lds_dwordx4 v[244:245], off
	s_cmp_lg_u32 s1, 1
	v_writelane_b32 v241, s38, 58
	s_cbranch_scc1 .LBB0_268
	s_barrier
.LBB0_268:
	s_lshl_b64 s[4:5], s[4:5], 2
	v_readlane_b32 s0, v241, 43
	s_add_u32 s58, s0, s4
	v_readlane_b32 s0, v241, 44
	s_addc_u32 s92, s0, s5
	v_bfe_u32 v67, v14, 4, 2
	s_add_u32 s93, s74, 0xe400000
	s_waitcnt vmcnt(0)
	v_and_b32_e32 v164, 15, v14
	v_lshlrev_b32_e32 v21, 4, v67
	v_lshlrev_b32_e32 v14, 2, v14
	s_addc_u32 s53, s75, 0
	s_lshl_b32 s0, s1, 6
	v_lshl_or_b32 v21, v164, 6, v21
	s_lshl_b32 s1, s1, 13
	v_and_b32_e32 v14, 32, v14
	v_bitop3_b32 v22, v21, s1, v14 bitop3:0xde
	s_lshl_b32 s1, s17, 5
	s_and_b32 s1, s1, 0x60
	v_readlane_b32 s2, v242, 11
	s_lshl_b32 s4, s1, 7
	v_readlane_b32 s3, v242, 12
	s_andn2_b64 s[2:3], s[2:3], s[100:101]
	v_bitop3_b32 v165, v21, s4, v14 bitop3:0xde
	s_and_b64 s[4:5], s[2:3], exec
	s_cselect_b32 s84, 0, s16
	s_add_i32 m0, s63, 0x18000
	v_lshl_add_u64 v[2:3], v[2:3], 0, s[18:19]
	s_waitcnt vmcnt(2)
	s_barrier
	v_lshl_add_u64 v[2:3], v[4:5], 0, s[18:19]
	s_add_i32 m0, s63, 0x1a000
	s_add_i32 s23, s63, 0x8000
	v_lshl_add_u64 v[2:3], v[10:11], 0, s[18:19]
	s_mov_b32 m0, s23
	s_add_i32 s62, s63, 0xa000
	v_lshl_add_u64 v[2:3], v[12:13], 0, s[18:19]
	s_mov_b32 m0, s62
	s_mov_b32 s7, s6
	s_add_i32 m0, s63, 0x1c000
	v_lshl_add_u64 v[2:3], v[6:7], 0, s[18:19]
	v_lshl_add_u64 v[2:3], v[8:9], 0, s[18:19]
	s_add_i32 m0, s63, 0x1e000
	s_cmpk_lt_u32 s10, 0x100
	v_add_u32_e32 v2, v17, v15
	v_add_lshl_u32 v2, v2, v16, 1
	v_mov_b32_e32 v3, v185
	s_waitcnt vmcnt(6)
	v_lshl_add_u64 v[146:147], s[78:79], 0, v[2:3]
	v_add_u32_e32 v2, v20, v18
	v_add_lshl_u32 v2, v2, v19, 1
	s_mov_b32 s88, s6
	s_mov_b32 s89, s6
	s_mov_b32 s22, 0
	s_cselect_b64 s[94:95], -1, 0
	s_add_i32 s10, s50, 2
	v_lshl_add_u64 v[148:149], s[78:79], 0, v[2:3]
	v_add_u32_e32 v166, 0, v22
	s_barrier
	s_branch .LBB0_271

.LBB0_432:
	v_bfe_u32 v146, v8, 4, 2
	v_and_b32_e32 v67, 15, v8
	v_lshlrev_b32_e32 v9, 4, v146
	v_lshlrev_b32_e32 v8, 2, v8
	s_sext_i32_i8 s50, s6
	v_lshl_or_b32 v9, v67, 6, v9
	s_lshl_b32 s6, s20, 13
	v_and_b32_e32 v8, 32, v8
	v_bitop3_b32 v18, v9, s6, v8 bitop3:0xde
	s_lshl_b32 s6, s7, 5
	s_and_b32 s41, s6, 0x60
	v_lshl_add_u64 v[10:11], s[30:31], 0, v[184:185]
	v_mov_b32_e32 v133, v185
	s_lshl_b32 s6, s41, 7
	v_lshl_add_u64 v[12:13], s[30:31], 0, v[132:133]
	v_mov_b32_e32 v137, v185
	v_bitop3_b32 v147, v9, s6, v8 bitop3:0xde
	s_add_i32 m0, s5, 0x18000
	v_lshl_add_u64 v[8:9], v[10:11], 0, s[18:19]
	v_lshl_add_u64 v[14:15], s[28:29], 0, v[136:137]
	v_mov_b32_e32 v135, v185
	s_lshl_b32 s40, s20, 6
	global_load_lds_dwordx4 v[8:9], off
	v_lshl_add_u64 v[8:9], v[12:13], 0, s[18:19]
	s_add_i32 m0, s5, 0x1a000
	s_add_i32 s42, s5, 0x8000
	s_add_i32 s43, s5, 0xa000
	v_lshl_add_u64 v[16:17], s[28:29], 0, v[134:135]
	global_load_lds_dwordx4 v[8:9], off
	v_lshl_add_u64 v[8:9], v[14:15], 0, s[18:19]
	s_mov_b32 m0, s42
	s_add_u32 s6, s30, 0x40080
	global_load_lds_dwordx4 v[8:9], off
	v_lshl_add_u64 v[8:9], v[16:17], 0, s[18:19]
	s_mov_b32 m0, s43
	s_addc_u32 s7, s31, 0
	global_load_lds_dwordx4 v[8:9], off
	s_add_i32 m0, s5, 0x1c000
	v_lshl_add_u64 v[8:9], s[6:7], 0, v[184:185]
	global_load_lds_dwordx4 v[8:9], off
	v_lshl_add_u64 v[8:9], s[6:7], 0, v[132:133]
	s_add_i32 m0, s5, 0x1e000
	v_mov_b32_e32 v139, v185
	global_load_lds_dwordx4 v[8:9], off
	s_waitcnt vmcnt(8)
	s_barrier
	v_lshlrev_b32_e32 v8, 14, v6
	v_and_b32_e32 v8, 0xffff8000, v8
	v_lshl_add_u32 v5, v5, 11, v8
	v_and_b32_e32 v6, 1, v6
	v_lshl_or_b32 v5, v6, 6, v5
	v_lshl_add_u32 v138, v7, 1, v5
	v_lshlrev_b32_e32 v5, 14, v2
	v_and_b32_e32 v5, 0xffff8000, v5
	s_waitcnt vmcnt(6)
	v_lshl_add_u32 v3, v3, 11, v5
	v_and_b32_e32 v2, 1, v2
	v_lshl_or_b32 v2, v2, 6, v3
	v_lshl_add_u32 v140, v4, 1, v2
	v_mov_b32_e32 v141, v185
	s_mov_b32 s49, 0
	s_waitcnt vmcnt(0)
	v_add_u32_e32 v148, 0, v18
	s_barrier
